# grid barrier: non-leader workgroups poll the cross-XCD release word directly instead of waiting for the per-XCD hand-off (one hop fewer per barrier)
# speedup vs baseline: 1.0058x; 1.0028x over previous
.LBB0_224:
	s_or_b64 exec, exec, s[10:11]
	v_cvt_f32_u32_e32 v4, v2
	s_waitcnt vmcnt(0)
	v_readfirstlane_b32 s3, v3
	v_sub_u32_e32 v3, 0, v2
	v_rcp_iflag_f32_e32 v4, v4
	v_add_u32_e32 v5, s3, v1
	v_mul_f32_e32 v4, 0x4f7ffffe, v4
	v_cvt_u32_f32_e32 v4, v4
	v_mul_lo_u32 v1, v3, v4
	v_mul_hi_u32 v1, v4, v1
	v_add_u32_e32 v1, v4, v1
	v_mul_hi_u32 v1, v5, v1
	v_mul_lo_u32 v3, v1, v2
	v_sub_u32_e32 v3, v5, v3
	v_add_u32_e32 v4, 1, v1
	v_cmp_ge_u32_e32 vcc, v3, v2
	s_nop 1
	v_cndmask_b32_e32 v1, v1, v4, vcc
	v_sub_u32_e32 v4, v3, v2
	v_cndmask_b32_e32 v3, v3, v4, vcc
	v_add_u32_e32 v4, 1, v1
	v_cmp_ge_u32_e32 vcc, v3, v2
	v_add_u32_e32 v3, 1, v5
	s_nop 0
	v_cndmask_b32_e32 v1, v1, v4, vcc
	v_mul_lo_u32 v4, v2, v1
	v_add_u32_e32 v2, v4, v2
	v_cmp_ne_u32_e32 vcc, v3, v2
	s_and_saveexec_b64 s[8:9], vcc
	s_xor_b64 s[8:9], exec, s[8:9]
	s_cbranch_execz .LBB0_238
	s_waitcnt lgkmcnt(0)
	s_add_u32 s14, s26, 0x1e704500
	s_addc_u32 s15, s27, 0
	v_mov_b32_e32 v0, 0
	global_load_dword v0, v0, s[14:15] sc1
	s_waitcnt vmcnt(0)
	v_cmp_eq_u32_e32 vcc, v0, v1
	s_and_saveexec_b64 s[10:11], vcc
	s_cbranch_execz .LBB0_237
	s_add_u32 s12, s26, 0x1e701200
	s_addc_u32 s13, s27, 0
	s_mov_b32 s3, 1
	s_mov_b64 s[20:21], 0
	v_mov_b32_e32 v0, 0
	s_branch .LBB0_228

.LBB0_369:
	s_or_b64 exec, exec, s[20:21]
	v_cvt_f32_u32_e32 v4, v2
	s_waitcnt vmcnt(0)
	v_readfirstlane_b32 s3, v3
	v_sub_u32_e32 v3, 0, v2
	v_rcp_iflag_f32_e32 v4, v4
	v_add_u32_e32 v5, s3, v1
	v_mul_f32_e32 v4, 0x4f7ffffe, v4
	v_cvt_u32_f32_e32 v4, v4
	v_mul_lo_u32 v1, v3, v4
	v_mul_hi_u32 v1, v4, v1
	v_add_u32_e32 v1, v4, v1
	v_mul_hi_u32 v1, v5, v1
	v_mul_lo_u32 v3, v1, v2
	v_sub_u32_e32 v3, v5, v3
	v_add_u32_e32 v4, 1, v1
	v_cmp_ge_u32_e32 vcc, v3, v2
	s_nop 1
	v_cndmask_b32_e32 v1, v1, v4, vcc
	v_sub_u32_e32 v4, v3, v2
	v_cndmask_b32_e32 v3, v3, v4, vcc
	v_add_u32_e32 v4, 1, v1
	v_cmp_ge_u32_e32 vcc, v3, v2
	v_add_u32_e32 v3, 1, v5
	s_nop 0
	v_cndmask_b32_e32 v1, v1, v4, vcc
	v_mul_lo_u32 v4, v2, v1
	v_add_u32_e32 v2, v4, v2
	v_cmp_ne_u32_e32 vcc, v3, v2
	s_and_saveexec_b64 s[10:11], vcc
	s_xor_b64 s[10:11], exec, s[10:11]
	s_cbranch_execz .LBB0_383
	s_waitcnt lgkmcnt(0)
	s_add_u32 s36, s26, 0x1e704500
	s_addc_u32 s37, s27, 0
	v_mov_b32_e32 v0, 0
	global_load_dword v0, v0, s[36:37] sc1
	s_waitcnt vmcnt(0)
	v_cmp_eq_u32_e32 vcc, v0, v1
	s_and_saveexec_b64 s[20:21], vcc
	s_cbranch_execz .LBB0_382
	s_add_u32 s28, s26, 0x1e701200
	s_addc_u32 s29, s27, 0
	s_mov_b32 s3, 1
	s_mov_b64 s[38:39], 0
	v_mov_b32_e32 v0, 0
	s_branch .LBB0_373

.LBB0_500:
	s_or_b64 exec, exec, s[10:11]
	v_cvt_f32_u32_e32 v4, v2
	s_waitcnt vmcnt(0)
	v_readfirstlane_b32 s3, v3
	v_sub_u32_e32 v3, 0, v2
	v_rcp_iflag_f32_e32 v4, v4
	v_add_u32_e32 v5, s3, v1
	v_mul_f32_e32 v4, 0x4f7ffffe, v4
	v_cvt_u32_f32_e32 v4, v4
	v_mul_lo_u32 v1, v3, v4
	v_mul_hi_u32 v1, v4, v1
	v_add_u32_e32 v1, v4, v1
	v_mul_hi_u32 v1, v5, v1
	v_mul_lo_u32 v3, v1, v2
	v_sub_u32_e32 v3, v5, v3
	v_add_u32_e32 v4, 1, v1
	v_cmp_ge_u32_e32 vcc, v3, v2
	s_nop 1
	v_cndmask_b32_e32 v1, v1, v4, vcc
	v_sub_u32_e32 v4, v3, v2
	v_cndmask_b32_e32 v3, v3, v4, vcc
	v_add_u32_e32 v4, 1, v1
	v_cmp_ge_u32_e32 vcc, v3, v2
	v_add_u32_e32 v3, 1, v5
	s_nop 0
	v_cndmask_b32_e32 v1, v1, v4, vcc
	v_mul_lo_u32 v4, v2, v1
	v_add_u32_e32 v2, v4, v2
	v_cmp_ne_u32_e32 vcc, v3, v2
	s_and_saveexec_b64 s[8:9], vcc
	s_xor_b64 s[8:9], exec, s[8:9]
	s_cbranch_execz .LBB0_514
	s_waitcnt lgkmcnt(0)
	s_add_u32 s28, s26, 0x1e704500
	s_addc_u32 s29, s27, 0
	v_mov_b32_e32 v0, 0
	global_load_dword v0, v0, s[28:29] sc1
	s_waitcnt vmcnt(0)
	v_cmp_eq_u32_e32 vcc, v0, v1
	s_and_saveexec_b64 s[10:11], vcc
	s_cbranch_execz .LBB0_513
	s_add_u32 s20, s26, 0x1e701200
	s_addc_u32 s21, s27, 0
	s_mov_b32 s3, 1
	s_mov_b64 s[36:37], 0
	v_mov_b32_e32 v0, 0
	s_branch .LBB0_504

.LBB0_765:
	s_or_b64 exec, exec, s[8:9]
	v_cvt_f32_u32_e32 v4, v2
	s_waitcnt vmcnt(0)
	v_readfirstlane_b32 s3, v3
	v_sub_u32_e32 v3, 0, v2
	v_rcp_iflag_f32_e32 v4, v4
	v_add_u32_e32 v5, s3, v1
	v_mul_f32_e32 v4, 0x4f7ffffe, v4
	v_cvt_u32_f32_e32 v4, v4
	v_mul_lo_u32 v1, v3, v4
	v_mul_hi_u32 v1, v4, v1
	v_add_u32_e32 v1, v4, v1
	v_mul_hi_u32 v1, v5, v1
	v_mul_lo_u32 v3, v1, v2
	v_sub_u32_e32 v3, v5, v3
	v_add_u32_e32 v4, 1, v1
	v_cmp_ge_u32_e32 vcc, v3, v2
	s_nop 1
	v_cndmask_b32_e32 v1, v1, v4, vcc
	v_sub_u32_e32 v4, v3, v2
	v_cndmask_b32_e32 v3, v3, v4, vcc
	v_add_u32_e32 v4, 1, v1
	v_cmp_ge_u32_e32 vcc, v3, v2
	v_add_u32_e32 v3, 1, v5
	s_nop 0
	v_cndmask_b32_e32 v1, v1, v4, vcc
	v_mul_lo_u32 v4, v2, v1
	v_add_u32_e32 v2, v4, v2
	v_cmp_ne_u32_e32 vcc, v3, v2
	s_and_saveexec_b64 s[6:7], vcc
	s_xor_b64 s[6:7], exec, s[6:7]
	s_cbranch_execz .LBB0_779
	s_waitcnt lgkmcnt(0)
	s_add_u32 s20, s26, 0x1e704500
	s_addc_u32 s21, s27, 0
	v_mov_b32_e32 v0, 0
	global_load_dword v0, v0, s[20:21] sc1
	s_waitcnt vmcnt(0)
	v_cmp_eq_u32_e32 vcc, v0, v1
	s_and_saveexec_b64 s[8:9], vcc
	s_cbranch_execz .LBB0_778
	s_add_u32 s10, s26, 0x1e701200
	s_addc_u32 s11, s27, 0
	s_mov_b32 s3, 1
	s_mov_b64 s[28:29], 0
	v_mov_b32_e32 v0, 0
	s_branch .LBB0_769

.LBB0_1061:
	s_or_b64 exec, exec, s[10:11]
	v_cvt_f32_u32_e32 v4, v2
	s_waitcnt vmcnt(0)
	v_readfirstlane_b32 s3, v3
	v_sub_u32_e32 v3, 0, v2
	v_rcp_iflag_f32_e32 v4, v4
	v_add_u32_e32 v5, s3, v1
	v_mul_f32_e32 v4, 0x4f7ffffe, v4
	v_cvt_u32_f32_e32 v4, v4
	v_mul_lo_u32 v1, v3, v4
	v_mul_hi_u32 v1, v4, v1
	v_add_u32_e32 v1, v4, v1
	v_mul_hi_u32 v1, v5, v1
	v_mul_lo_u32 v3, v1, v2
	v_sub_u32_e32 v3, v5, v3
	v_add_u32_e32 v4, 1, v1
	v_cmp_ge_u32_e32 vcc, v3, v2
	s_nop 1
	v_cndmask_b32_e32 v1, v1, v4, vcc
	v_sub_u32_e32 v4, v3, v2
	v_cndmask_b32_e32 v3, v3, v4, vcc
	v_add_u32_e32 v4, 1, v1
	v_cmp_ge_u32_e32 vcc, v3, v2
	v_add_u32_e32 v3, 1, v5
	s_nop 0
	v_cndmask_b32_e32 v1, v1, v4, vcc
	v_mul_lo_u32 v4, v2, v1
	v_add_u32_e32 v2, v4, v2
	v_cmp_ne_u32_e32 vcc, v3, v2
	s_and_saveexec_b64 s[8:9], vcc
	s_xor_b64 s[8:9], exec, s[8:9]
	s_cbranch_execz .LBB0_1075
	s_waitcnt lgkmcnt(0)
	s_add_u32 s18, s26, 0x1e704500
	s_addc_u32 s19, s27, 0
	v_mov_b32_e32 v0, 0
	global_load_dword v0, v0, s[18:19] sc1
	s_waitcnt vmcnt(0)
	v_cmp_eq_u32_e32 vcc, v0, v1
	s_and_saveexec_b64 s[10:11], vcc
	s_cbranch_execz .LBB0_1074
	s_add_u32 s16, s26, 0x1e701200
	s_addc_u32 s17, s27, 0
	s_mov_b32 s3, 1
	s_mov_b64 s[20:21], 0
	v_mov_b32_e32 v0, 0
	s_branch .LBB0_1065
